# P4 K loop: one address register pair per LDS-DMA with the address adds at the top of each load phase, plus a yield point after every 8 MFMAs
# speedup vs baseline: 1.0012x; 1.0012x over previous
; #define PG8_STAGE(bufoff, gbase, voff) do { _Pragma("unroll") for (int _i = 0; _i < 2; ++_i) \
;         __builtin_amdgcn_global_load_lds((const unsigned*)((const char*)(gbase) + (voff)[_i]), (PG8_LAS unsigned*)(lds + (bufoff) + ldsw + _i * 8192), 16, 0, 0); } while (0)
; #define PG8_LDA(dst, b, h) do { _Pragma("unroll") for (int m = 0; m < 4; ++m) _Pragma("unroll") for (int k = 0; k < 2; ++k) dst[m][k] = *(const PG8_LAS bf16x8*)(lds + PG8_SA(b, h) + aoff + m * 2048 + k * 1024); } while (0)
; #define PG8_LDB(dst, b, h) do { _Pragma("unroll") for (int n = 0; n < 2; ++n) _Pragma("unroll") for (int k = 0; k < 2; ++k) dst[n][k] = *(const PG8_LAS bf16x8*)(lds + PG8_SB(b, h) + boff + n * 2048 + k * 1024); } while (0)
; #define PG8_WAIT_V(n) asm volatile("s_waitcnt vmcnt(" #n ")" ::: "memory")
; #define PG8_WAIT_L(n) asm volatile("s_waitcnt lgkmcnt(" #n ")" ::: "memory")
; template <class Epi, class Sched, bool ALIGN_EPI = false, bool SP2 = false, bool ABLK = false>
; __device__ __forceinline__ void gemm_phase(PG8_LAS unsigned char* lds, const Gemm g, const Sched& S, const Epi& E) {
;     ...
;         const bool has_next = S.next(ui + 1, nxt);
;         const char* nA = has_next ? (const char*)g.A + (size_t)nxt.pm * tstepA : cA; const char* nB = has_next ? (const char*)g.Bt + (size_t)nxt.pn * tstep : cB;
;         for (int t = 0; t < nt; t += 2) {
;             if constexpr (Epi::MID) { if (t == nt / 2) E.mid(acc, cur, wr, wc, fr, fq); }
;             const bool last = (t == nt - 2);
;             const char* a1 = cA + (size_t)(t + 1) * kstepA;
;             const char* a2 = last ? nA : cA + (size_t)(t + 2) * kstepA; const char* b2 = last ? nB : cB + (size_t)(t + 2) * kstep;
;             const char* a3 = a2 + kstepA; const char* b3 = b2 + kstep;
;             if (last && has_next) S.a_ready(nxt);
;             if constexpr (SP2) {
;             PG8_LDB(B0, 0, 0); PG8_LDB(B1, 0, 1); PG8_SCHED; PG8_LDA(At, 0, 0); PG8_STAGE(PG8_SA(1, 1), a1 + hstepA, voffA);
;             PG8_WAIT_V(8); PG8_WAIT_L(0); PG8_BAR; PG8_MMA(0, 0, At, B0); PG8_MMA(0, 1, At, B1); PG8_BAR; PG8_SCHED;
;             PG8_LDA(At, 0, 1); PG8_STAGE(PG8_SB(0, 0), b2, voffB); PG8_STAGE(PG8_SB(0, 1), b2 + hstep, voffB); PG8_STAGE(PG8_SA(0, 0), a2, voffA);
;             PG8_WAIT_V(8); PG8_WAIT_L(0); PG8_BAR; PG8_MMA(1, 0, At, B0); PG8_MMA(1, 1, At, B1); PG8_BAR; PG8_SCHED;
.LBB0_533:
	s_ashr_i32 s21, s20, 31
	s_lshl_b64 s[8:9], s[20:21], 19
	s_add_u32 s24, s10, s8
	s_addc_u32 s25, s11, s9
	s_and_b64 s[8:9], s[26:27], exec
	s_cselect_b32 s7, s25, s37
	s_cselect_b32 s21, s24, s36
	s_ashr_i32 s23, s22, 31
	s_lshl_b64 s[8:9], s[22:23], 19
	s_add_u32 s28, s52, s8
	s_addc_u32 s29, s53, s9
	s_and_b64 s[8:9], s[26:27], exec
	s_cselect_b32 s23, s29, s35
	s_cselect_b32 s31, s28, s34
	s_add_u32 s61, s34, 0x100
	s_addc_u32 s62, s35, 0
	s_add_u32 s8, s36, 0xc000
	s_addc_u32 s9, s37, 0
	s_mov_b32 s63, -2
	ds_read_b128 v[128:131], v143
	ds_read_b128 v[176:179], v143 offset:1024
	ds_read_b128 v[180:183], v143 offset:2048
	ds_read_b128 v[184:187], v143 offset:3072
	ds_read_b128 v[188:191], v167
	ds_read_b128 v[192:195], v167 offset:1024
	ds_read_b128 v[196:199], v167 offset:2048
	ds_read_b128 v[200:203], v167 offset:3072
	s_add_u32 s2, s8, 0x4000
	s_addc_u32 s34, s9, 0
	s_cmp_eq_u32 s63, 12
	s_cselect_b32 s38, s21, s2
	s_cselect_b32 s39, s7, s34
	s_cselect_b32 s36, s31, s61
	s_cselect_b32 s37, s23, s62
	s_add_u32 s34, s38, 0x8000
	s_addc_u32 s35, s39, 0
	v_lshl_add_u64 v[172:173], s[8:9], 0, v[162:163]
	v_lshl_add_u64 v[240:241], s[8:9], 0, v[164:165]
	ds_read_b128 v[204:207], v168
	ds_read_b128 v[208:211], v168 offset:1024
	ds_read_b128 v[212:215], v168 offset:2048
	ds_read_b128 v[216:219], v168 offset:3072
	ds_read_b128 v[220:223], v168 offset:4096
	ds_read_b128 v[224:227], v168 offset:5120
	ds_read_b128 v[228:231], v168 offset:6144
	ds_read_b128 v[232:235], v168 offset:7168
	s_mov_b32 m0, s58
	s_nop 0
	global_load_lds_dwordx4 v[172:173], off
	s_mov_b32 m0, s59
	s_nop 0
	global_load_lds_dwordx4 v[240:241], off
	s_waitcnt vmcnt(8)
	s_waitcnt lgkmcnt(0)
	s_barrier
	s_setprio 1
	s_waitcnt lgkmcnt(0)
	v_mfma_f32_16x16x32_bf16 v[124:127], v[128:131], v[204:207], 0
	v_mfma_f32_16x16x32_bf16 v[120:123], v[180:183], v[204:207], 0
	v_mfma_f32_16x16x32_bf16 v[108:111], v[128:131], v[212:215], 0
	v_mfma_f32_16x16x32_bf16 v[104:107], v[180:183], v[212:215], 0
	v_mfma_f32_16x16x32_bf16 v[92:95], v[128:131], v[220:223], 0
	v_mfma_f32_16x16x32_bf16 v[88:91], v[180:183], v[220:223], 0
	v_mfma_f32_16x16x32_bf16 v[76:79], v[128:131], v[228:231], 0
	v_mfma_f32_16x16x32_bf16 v[72:75], v[180:183], v[228:231], 0
	v_mfma_f32_16x16x32_bf16 v[124:127], v[176:179], v[208:211], v[124:127]
	v_mfma_f32_16x16x32_bf16 v[120:123], v[184:187], v[208:211], v[120:123]
	v_mfma_f32_16x16x32_bf16 v[108:111], v[176:179], v[216:219], v[108:111]
	v_mfma_f32_16x16x32_bf16 v[104:107], v[184:187], v[216:219], v[104:107]
	v_mfma_f32_16x16x32_bf16 v[92:95], v[176:179], v[224:227], v[92:95]
	v_mfma_f32_16x16x32_bf16 v[88:91], v[184:187], v[224:227], v[88:91]
	v_mfma_f32_16x16x32_bf16 v[76:79], v[176:179], v[232:235], v[76:79]
	v_mfma_f32_16x16x32_bf16 v[72:75], v[184:187], v[232:235], v[72:75]
	s_setprio 0
	s_setprio 1
	v_mfma_f32_16x16x32_bf16 v[116:119], v[188:191], v[204:207], 0
	v_mfma_f32_16x16x32_bf16 v[112:115], v[196:199], v[204:207], 0
	v_mfma_f32_16x16x32_bf16 v[100:103], v[188:191], v[212:215], 0
	v_mfma_f32_16x16x32_bf16 v[96:99], v[196:199], v[212:215], 0
	v_mfma_f32_16x16x32_bf16 v[84:87], v[188:191], v[220:223], 0
	v_mfma_f32_16x16x32_bf16 v[80:83], v[196:199], v[220:223], 0
	v_mfma_f32_16x16x32_bf16 v[68:71], v[188:191], v[228:231], 0
	v_mfma_f32_16x16x32_bf16 v[64:67], v[196:199], v[228:231], 0
	v_mfma_f32_16x16x32_bf16 v[116:119], v[192:195], v[208:211], v[116:119]
	v_mfma_f32_16x16x32_bf16 v[112:115], v[200:203], v[208:211], v[112:115]
	v_mfma_f32_16x16x32_bf16 v[100:103], v[192:195], v[216:219], v[100:103]
	v_mfma_f32_16x16x32_bf16 v[96:99], v[200:203], v[216:219], v[96:99]
	v_mfma_f32_16x16x32_bf16 v[84:87], v[192:195], v[224:227], v[84:87]
	v_mfma_f32_16x16x32_bf16 v[80:83], v[200:203], v[224:227], v[80:83]
	v_mfma_f32_16x16x32_bf16 v[68:71], v[192:195], v[232:235], v[68:71]
	v_mfma_f32_16x16x32_bf16 v[64:67], v[200:203], v[232:235], v[64:67]
	s_setprio 0
	s_barrier
	s_add_u32 s70, s36, 0x40000
	s_addc_u32 s71, s37, 0
	s_add_i32 s2, s57, s3
	v_lshl_add_u64 v[172:173], s[36:37], 0, v[136:137]
	v_lshl_add_u64 v[236:237], s[36:37], 0, v[132:133]
	v_lshl_add_u64 v[238:239], s[70:71], 0, v[136:137]
	v_lshl_add_u64 v[240:241], s[70:71], 0, v[132:133]
	v_lshl_add_u64 v[242:243], s[38:39], 0, v[138:139]
	v_lshl_add_u64 v[254:255], s[38:39], 0, v[134:135]
	ds_read_b128 v[204:207], v168 offset:16384
	ds_read_b128 v[208:211], v168 offset:17408
	ds_read_b128 v[212:215], v168 offset:18432
	ds_read_b128 v[216:219], v168 offset:19456
	ds_read_b128 v[220:223], v168 offset:20480
	ds_read_b128 v[224:227], v168 offset:21504
	ds_read_b128 v[228:231], v168 offset:22528
	ds_read_b128 v[232:235], v168 offset:23552
	s_mov_b32 m0, s60
	s_nop 0
	global_load_lds_dwordx4 v[172:173], off
	s_add_i32 m0, s60, 0x2000
	s_nop 0
	global_load_lds_dwordx4 v[236:237], off
	s_mov_b32 m0, s2
	s_nop 0
	global_load_lds_dwordx4 v[238:239], off
	s_add_i32 m0, s2, 0x2000
	s_nop 0
	global_load_lds_dwordx4 v[240:241], off
	s_mov_b32 m0, s40
	s_nop 0
	global_load_lds_dwordx4 v[242:243], off
	s_mov_b32 m0, s41
	s_nop 0
	global_load_lds_dwordx4 v[254:255], off
	s_waitcnt vmcnt(8)
	s_waitcnt lgkmcnt(0)
	s_barrier
; #define PG8_STAGE(bufoff, gbase, voff) do { _Pragma("unroll") for (int _i = 0; _i < 2; ++_i) \
;         __builtin_amdgcn_global_load_lds((const unsigned*)((const char*)(gbase) + (voff)[_i]), (PG8_LAS unsigned*)(lds + (bufoff) + ldsw + _i * 8192), 16, 0, 0); } while (0)
; #define PG8_LDA(dst, b, h) do { _Pragma("unroll") for (int m = 0; m < 4; ++m) _Pragma("unroll") for (int k = 0; k < 2; ++k) dst[m][k] = *(const PG8_LAS bf16x8*)(lds + PG8_SA(b, h) + aoff + m * 2048 + k * 1024); } while (0)
; #define PG8_LDB(dst, b, h) do { _Pragma("unroll") for (int n = 0; n < 2; ++n) _Pragma("unroll") for (int k = 0; k < 2; ++k) dst[n][k] = *(const PG8_LAS bf16x8*)(lds + PG8_SB(b, h) + boff + n * 2048 + k * 1024); } while (0)
; #define PG8_MMA(ai, bj, At, Bt) do { __builtin_amdgcn_s_setprio(1); _Pragma("unroll") for (int m = 0; m < 4; ++m) _Pragma("unroll") for (int n = 0; n < 2; ++n) _Pragma("unroll") for (int k = 0; k < 2; ++k) \
;         acc[ai][bj][m][n] = __builtin_amdgcn_mfma_f32_16x16x32_bf16(Bt[n][k], At[m][k], acc[ai][bj][m][n], 0, 0, 0); __builtin_amdgcn_s_setprio(0); } while (0)
; #define PG8_WAIT_V(n) asm volatile("s_waitcnt vmcnt(" #n ")" ::: "memory")
; #define PG8_WAIT_L(n) asm volatile("s_waitcnt lgkmcnt(" #n ")" ::: "memory")
; #define PG8_BAR __builtin_amdgcn_s_barrier()
; #define PG8_SCHED __builtin_amdgcn_sched_barrier(0)
; template <class Epi, class Sched, bool ALIGN_EPI = false, bool SP2 = false, bool ABLK = false>
; __device__ __forceinline__ void gemm_phase(PG8_LAS unsigned char* lds, const Gemm g, const Sched& S, const Epi& E) {
;     ...
;             PG8_WAIT_V(8); PG8_WAIT_L(0); PG8_BAR; PG8_MMA(1, 0, At, B0); PG8_MMA(1, 1, At, B1); PG8_BAR; PG8_SCHED;
;             PG8_LDB(B0, 1, 0); PG8_LDB(B1, 1, 1); PG8_SCHED; PG8_LDA(At, 1, 0); PG8_STAGE(PG8_SA(0, 1), a2 + hstepA, voffA);
;             PG8_WAIT_V(8); PG8_WAIT_L(0); PG8_BAR; PG8_MMA(0, 0, At, B0); PG8_MMA(0, 1, At, B1); PG8_BAR; PG8_SCHED;
	s_setprio 1
	s_waitcnt lgkmcnt(0)
	v_mfma_f32_16x16x32_bf16 v[60:63], v[128:131], v[204:207], 0
	v_mfma_f32_16x16x32_bf16 v[56:59], v[180:183], v[204:207], 0
	v_mfma_f32_16x16x32_bf16 v[44:47], v[128:131], v[212:215], 0
	v_mfma_f32_16x16x32_bf16 v[40:43], v[180:183], v[212:215], 0
	v_mfma_f32_16x16x32_bf16 v[28:31], v[128:131], v[220:223], 0
	v_mfma_f32_16x16x32_bf16 v[24:27], v[180:183], v[220:223], 0
	v_mfma_f32_16x16x32_bf16 v[12:15], v[128:131], v[228:231], 0
	v_mfma_f32_16x16x32_bf16 v[8:11], v[180:183], v[228:231], 0
	v_mfma_f32_16x16x32_bf16 v[60:63], v[176:179], v[208:211], v[60:63]
	v_mfma_f32_16x16x32_bf16 v[56:59], v[184:187], v[208:211], v[56:59]
	v_mfma_f32_16x16x32_bf16 v[44:47], v[176:179], v[216:219], v[44:47]
	v_mfma_f32_16x16x32_bf16 v[40:43], v[184:187], v[216:219], v[40:43]
	v_mfma_f32_16x16x32_bf16 v[28:31], v[176:179], v[224:227], v[28:31]
	v_mfma_f32_16x16x32_bf16 v[24:27], v[184:187], v[224:227], v[24:27]
	v_mfma_f32_16x16x32_bf16 v[12:15], v[176:179], v[232:235], v[12:15]
	v_mfma_f32_16x16x32_bf16 v[8:11], v[184:187], v[232:235], v[8:11]
	s_setprio 0
	s_setprio 1
	v_mfma_f32_16x16x32_bf16 v[52:55], v[188:191], v[204:207], 0
	v_mfma_f32_16x16x32_bf16 v[48:51], v[196:199], v[204:207], 0
	v_mfma_f32_16x16x32_bf16 v[36:39], v[188:191], v[212:215], 0
	v_mfma_f32_16x16x32_bf16 v[32:35], v[196:199], v[212:215], 0
	v_mfma_f32_16x16x32_bf16 v[20:23], v[188:191], v[220:223], 0
	v_mfma_f32_16x16x32_bf16 v[16:19], v[196:199], v[220:223], 0
	v_mfma_f32_16x16x32_bf16 v[4:7], v[188:191], v[228:231], 0
	v_mfma_f32_16x16x32_bf16 v[0:3], v[196:199], v[228:231], 0
	v_mfma_f32_16x16x32_bf16 v[52:55], v[192:195], v[208:211], v[52:55]
	v_mfma_f32_16x16x32_bf16 v[48:51], v[200:203], v[208:211], v[48:51]
	v_mfma_f32_16x16x32_bf16 v[36:39], v[192:195], v[216:219], v[36:39]
	v_mfma_f32_16x16x32_bf16 v[32:35], v[200:203], v[216:219], v[32:35]
	v_mfma_f32_16x16x32_bf16 v[20:23], v[192:195], v[224:227], v[20:23]
	v_mfma_f32_16x16x32_bf16 v[16:19], v[200:203], v[224:227], v[16:19]
	v_mfma_f32_16x16x32_bf16 v[4:7], v[192:195], v[232:235], v[4:7]
	v_mfma_f32_16x16x32_bf16 v[0:3], v[200:203], v[232:235], v[0:3]
	s_setprio 0
	s_barrier
	s_add_i32 s2, 0, 0x18000
	v_add_u32_e32 v171, s2, v166
	s_add_i32 s70, 0, 0x1c000
	ds_read_b128 v[128:131], v171
	ds_read_b128 v[176:179], v171 offset:1024
	ds_read_b128 v[180:183], v171 offset:2048
	ds_read_b128 v[184:187], v171 offset:3072
	v_add_u32_e32 v171, s70, v166
	ds_read_b128 v[188:191], v171
	ds_read_b128 v[192:195], v171 offset:1024
	ds_read_b128 v[196:199], v171 offset:2048
	ds_read_b128 v[200:203], v171 offset:3072
	s_add_u32 s38, s38, 0x4000
	s_addc_u32 s39, s39, 0
	v_lshl_add_u64 v[238:239], s[38:39], 0, v[138:139]
	v_lshl_add_u64 v[240:241], s[38:39], 0, v[134:135]
	ds_read_b128 v[204:207], v168 offset:32768
	ds_read_b128 v[208:211], v168 offset:33792
	ds_read_b128 v[212:215], v168 offset:34816
	ds_read_b128 v[216:219], v168 offset:35840
	ds_read_b128 v[220:223], v168 offset:36864
	ds_read_b128 v[224:227], v168 offset:37888
	ds_read_b128 v[228:231], v168 offset:38912
	ds_read_b128 v[232:235], v168 offset:39936
	s_mov_b32 m0, s44
	s_nop 0
	global_load_lds_dwordx4 v[238:239], off
	s_mov_b32 m0, s45
	s_nop 0
	global_load_lds_dwordx4 v[240:241], off
	s_waitcnt vmcnt(8)
	s_waitcnt lgkmcnt(0)
	s_barrier
	s_setprio 1
	s_waitcnt lgkmcnt(0)
	v_mfma_f32_16x16x32_bf16 v[124:127], v[128:131], v[204:207], v[124:127]
	v_mfma_f32_16x16x32_bf16 v[120:123], v[180:183], v[204:207], v[120:123]
	v_mfma_f32_16x16x32_bf16 v[108:111], v[128:131], v[212:215], v[108:111]
	v_mfma_f32_16x16x32_bf16 v[104:107], v[180:183], v[212:215], v[104:107]
	v_mfma_f32_16x16x32_bf16 v[92:95], v[128:131], v[220:223], v[92:95]
	v_mfma_f32_16x16x32_bf16 v[88:91], v[180:183], v[220:223], v[88:91]
	v_mfma_f32_16x16x32_bf16 v[76:79], v[128:131], v[228:231], v[76:79]
	v_mfma_f32_16x16x32_bf16 v[72:75], v[180:183], v[228:231], v[72:75]
	v_mfma_f32_16x16x32_bf16 v[124:127], v[176:179], v[208:211], v[124:127]
	v_mfma_f32_16x16x32_bf16 v[120:123], v[184:187], v[208:211], v[120:123]
	v_mfma_f32_16x16x32_bf16 v[108:111], v[176:179], v[216:219], v[108:111]
	v_mfma_f32_16x16x32_bf16 v[104:107], v[184:187], v[216:219], v[104:107]
	v_mfma_f32_16x16x32_bf16 v[92:95], v[176:179], v[224:227], v[92:95]
	v_mfma_f32_16x16x32_bf16 v[88:91], v[184:187], v[224:227], v[88:91]
	v_mfma_f32_16x16x32_bf16 v[76:79], v[176:179], v[232:235], v[76:79]
	v_mfma_f32_16x16x32_bf16 v[72:75], v[184:187], v[232:235], v[72:75]
	s_setprio 0
	s_setprio 1
	v_mfma_f32_16x16x32_bf16 v[116:119], v[188:191], v[204:207], v[116:119]
	v_mfma_f32_16x16x32_bf16 v[112:115], v[196:199], v[204:207], v[112:115]
	v_mfma_f32_16x16x32_bf16 v[100:103], v[188:191], v[212:215], v[100:103]
	v_mfma_f32_16x16x32_bf16 v[96:99], v[196:199], v[212:215], v[96:99]
	v_mfma_f32_16x16x32_bf16 v[84:87], v[188:191], v[220:223], v[84:87]
	v_mfma_f32_16x16x32_bf16 v[80:83], v[196:199], v[220:223], v[80:83]
	v_mfma_f32_16x16x32_bf16 v[68:71], v[188:191], v[228:231], v[68:71]
	v_mfma_f32_16x16x32_bf16 v[64:67], v[196:199], v[228:231], v[64:67]
	v_mfma_f32_16x16x32_bf16 v[116:119], v[192:195], v[208:211], v[116:119]
	v_mfma_f32_16x16x32_bf16 v[112:115], v[200:203], v[208:211], v[112:115]
	v_mfma_f32_16x16x32_bf16 v[100:103], v[192:195], v[216:219], v[100:103]
	v_mfma_f32_16x16x32_bf16 v[96:99], v[200:203], v[216:219], v[96:99]
	v_mfma_f32_16x16x32_bf16 v[84:87], v[192:195], v[224:227], v[84:87]
	v_mfma_f32_16x16x32_bf16 v[80:83], v[200:203], v[224:227], v[80:83]
	v_mfma_f32_16x16x32_bf16 v[68:71], v[192:195], v[232:235], v[68:71]
	v_mfma_f32_16x16x32_bf16 v[64:67], v[200:203], v[232:235], v[64:67]
	s_setprio 0
	s_barrier
; #define PG8_STAGE(bufoff, gbase, voff) do { _Pragma("unroll") for (int _i = 0; _i < 2; ++_i) \
;         __builtin_amdgcn_global_load_lds((const unsigned*)((const char*)(gbase) + (voff)[_i]), (PG8_LAS unsigned*)(lds + (bufoff) + ldsw + _i * 8192), 16, 0, 0); } while (0)
; #define PG8_LDA(dst, b, h) do { _Pragma("unroll") for (int m = 0; m < 4; ++m) _Pragma("unroll") for (int k = 0; k < 2; ++k) dst[m][k] = *(const PG8_LAS bf16x8*)(lds + PG8_SA(b, h) + aoff + m * 2048 + k * 1024); } while (0)
; #define PG8_LDB(dst, b, h) do { _Pragma("unroll") for (int n = 0; n < 2; ++n) _Pragma("unroll") for (int k = 0; k < 2; ++k) dst[n][k] = *(const PG8_LAS bf16x8*)(lds + PG8_SB(b, h) + boff + n * 2048 + k * 1024); } while (0)
; #define PG8_MMA(ai, bj, At, Bt) do { __builtin_amdgcn_s_setprio(1); _Pragma("unroll") for (int m = 0; m < 4; ++m) _Pragma("unroll") for (int n = 0; n < 2; ++n) _Pragma("unroll") for (int k = 0; k < 2; ++k) \
;         acc[ai][bj][m][n] = __builtin_amdgcn_mfma_f32_16x16x32_bf16(Bt[n][k], At[m][k], acc[ai][bj][m][n], 0, 0, 0); __builtin_amdgcn_s_setprio(0); } while (0)
; #define PG8_WAIT_V(n) asm volatile("s_waitcnt vmcnt(" #n ")" ::: "memory")
; #define PG8_WAIT_L(n) asm volatile("s_waitcnt lgkmcnt(" #n ")" ::: "memory")
; #define PG8_BAR __builtin_amdgcn_s_barrier()
; #define PG8_SCHED __builtin_amdgcn_sched_barrier(0)
; template <class Epi, class Sched, bool ALIGN_EPI = false, bool SP2 = false, bool ABLK = false>
; __device__ __forceinline__ void gemm_phase(PG8_LAS unsigned char* lds, const Gemm g, const Sched& S, const Epi& E) {
;     ...
;             PG8_LDB(B0, 0, 0); PG8_LDB(B1, 0, 1); PG8_SCHED; PG8_LDA(At, 0, 0); PG8_STAGE(PG8_SA(1, 1), a1 + hstepA, voffA);
;             PG8_WAIT_V(8); PG8_WAIT_L(0); PG8_BAR; PG8_MMA(0, 0, At, B0); PG8_MMA(0, 1, At, B1); PG8_BAR; PG8_SCHED;
;     ...
;             PG8_LDA(At, 1, 1); PG8_STAGE(PG8_SB(1, 0), b3, voffB); PG8_STAGE(PG8_SB(1, 1), b3 + hstep, voffB); PG8_STAGE(PG8_SA(1, 0), a3, voffA);
;             PG8_WAIT_V(8); PG8_WAIT_L(0); PG8_BAR; PG8_MMA(1, 0, At, B0); PG8_MMA(1, 1, At, B1); PG8_BAR; PG8_SCHED;
	s_add_i32 s2, s2, s3
	s_add_u32 s36, s36, 0x40080
	s_addc_u32 s37, s37, 0
	v_lshl_add_u64 v[172:173], v[172:173], 0, s[16:17]
	v_lshl_add_u64 v[236:237], v[236:237], 0, s[16:17]
	v_lshl_add_u64 v[238:239], s[36:37], 0, v[136:137]
	v_lshl_add_u64 v[240:241], s[36:37], 0, v[132:133]
	v_lshl_add_u64 v[242:243], s[34:35], 0, v[138:139]
	v_lshl_add_u64 v[254:255], s[34:35], 0, v[134:135]
	ds_read_b128 v[204:207], v168 offset:49152
	ds_read_b128 v[208:211], v168 offset:50176
	ds_read_b128 v[212:215], v168 offset:51200
	ds_read_b128 v[216:219], v168 offset:52224
	ds_read_b128 v[220:223], v168 offset:53248
	ds_read_b128 v[224:227], v168 offset:54272
	ds_read_b128 v[228:231], v168 offset:55296
	ds_read_b128 v[232:235], v168 offset:56320
	s_mov_b32 m0, s2
	s_nop 0
	global_load_lds_dwordx4 v[172:173], off
	s_add_i32 m0, s2, 0x2000
	s_nop 0
	global_load_lds_dwordx4 v[236:237], off
	s_add_i32 s2, s70, s3
	s_mov_b32 m0, s2
	s_nop 0
	global_load_lds_dwordx4 v[238:239], off
	s_add_i32 m0, s2, 0x2000
	s_nop 0
	global_load_lds_dwordx4 v[240:241], off
	s_mov_b32 m0, s55
	s_nop 0
	global_load_lds_dwordx4 v[242:243], off
	s_mov_b32 m0, s56
	s_nop 0
	global_load_lds_dwordx4 v[254:255], off
	s_waitcnt vmcnt(8)
	s_waitcnt lgkmcnt(0)
	s_barrier
	s_setprio 1
	s_waitcnt lgkmcnt(0)
	v_mfma_f32_16x16x32_bf16 v[60:63], v[128:131], v[204:207], v[60:63]
	v_mfma_f32_16x16x32_bf16 v[56:59], v[180:183], v[204:207], v[56:59]
	v_mfma_f32_16x16x32_bf16 v[44:47], v[128:131], v[212:215], v[44:47]
	v_mfma_f32_16x16x32_bf16 v[40:43], v[180:183], v[212:215], v[40:43]
	v_mfma_f32_16x16x32_bf16 v[28:31], v[128:131], v[220:223], v[28:31]
	v_mfma_f32_16x16x32_bf16 v[24:27], v[180:183], v[220:223], v[24:27]
	v_mfma_f32_16x16x32_bf16 v[12:15], v[128:131], v[228:231], v[12:15]
	v_mfma_f32_16x16x32_bf16 v[8:11], v[180:183], v[228:231], v[8:11]
	v_mfma_f32_16x16x32_bf16 v[60:63], v[176:179], v[208:211], v[60:63]
	v_mfma_f32_16x16x32_bf16 v[56:59], v[184:187], v[208:211], v[56:59]
	v_mfma_f32_16x16x32_bf16 v[44:47], v[176:179], v[216:219], v[44:47]
	v_mfma_f32_16x16x32_bf16 v[40:43], v[184:187], v[216:219], v[40:43]
	v_mfma_f32_16x16x32_bf16 v[28:31], v[176:179], v[224:227], v[28:31]
	v_mfma_f32_16x16x32_bf16 v[24:27], v[184:187], v[224:227], v[24:27]
	v_mfma_f32_16x16x32_bf16 v[12:15], v[176:179], v[232:235], v[12:15]
	v_mfma_f32_16x16x32_bf16 v[8:11], v[184:187], v[232:235], v[8:11]
	s_setprio 0
	s_setprio 1
	v_mfma_f32_16x16x32_bf16 v[52:55], v[188:191], v[204:207], v[52:55]
	v_mfma_f32_16x16x32_bf16 v[48:51], v[196:199], v[204:207], v[48:51]
	v_mfma_f32_16x16x32_bf16 v[36:39], v[188:191], v[212:215], v[36:39]
	v_mfma_f32_16x16x32_bf16 v[32:35], v[196:199], v[212:215], v[32:35]
	v_mfma_f32_16x16x32_bf16 v[20:23], v[188:191], v[220:223], v[20:23]
	v_mfma_f32_16x16x32_bf16 v[16:19], v[196:199], v[220:223], v[16:19]
	v_mfma_f32_16x16x32_bf16 v[4:7], v[188:191], v[228:231], v[4:7]
	v_mfma_f32_16x16x32_bf16 v[0:3], v[196:199], v[228:231], v[0:3]
	v_mfma_f32_16x16x32_bf16 v[52:55], v[192:195], v[208:211], v[52:55]
	v_mfma_f32_16x16x32_bf16 v[48:51], v[200:203], v[208:211], v[48:51]
	v_mfma_f32_16x16x32_bf16 v[36:39], v[192:195], v[216:219], v[36:39]
	v_mfma_f32_16x16x32_bf16 v[32:35], v[200:203], v[216:219], v[32:35]
	v_mfma_f32_16x16x32_bf16 v[20:23], v[192:195], v[224:227], v[20:23]
	v_mfma_f32_16x16x32_bf16 v[16:19], v[200:203], v[224:227], v[16:19]
	v_mfma_f32_16x16x32_bf16 v[4:7], v[192:195], v[232:235], v[4:7]
	v_mfma_f32_16x16x32_bf16 v[0:3], v[200:203], v[232:235], v[0:3]
	s_setprio 0
	s_barrier
	s_add_i32 s63, s63, 2
	s_add_u32 s61, s61, 0x100
	s_addc_u32 s62, s62, 0
	s_add_u32 s8, s8, 0x10000
	s_addc_u32 s9, s9, 0
	s_cmp_gt_u32 s63, 13
	s_cbranch_scc0 .LBB0_534
	s_branch .Lp4_kdone
.LBB0_534:
	ds_read_b128 v[128:131], v143
	ds_read_b128 v[176:179], v143 offset:1024
	ds_read_b128 v[180:183], v143 offset:2048
	ds_read_b128 v[184:187], v143 offset:3072
	ds_read_b128 v[188:191], v167
	ds_read_b128 v[192:195], v167 offset:1024
	ds_read_b128 v[196:199], v167 offset:2048
	ds_read_b128 v[200:203], v167 offset:3072
	s_add_u32 s2, s8, 0x4000
	s_addc_u32 s34, s9, 0
	s_cmp_eq_u32 s63, 12
	s_cselect_b32 s38, s21, s2
	s_cselect_b32 s39, s7, s34
	s_cselect_b32 s36, s31, s61
	s_cselect_b32 s37, s23, s62
	s_add_u32 s34, s38, 0x8000
	s_addc_u32 s35, s39, 0
	v_lshl_add_u64 v[172:173], s[8:9], 0, v[162:163]
	v_lshl_add_u64 v[240:241], s[8:9], 0, v[164:165]
	ds_read_b128 v[204:207], v168
	ds_read_b128 v[208:211], v168 offset:1024
	ds_read_b128 v[212:215], v168 offset:2048
	ds_read_b128 v[216:219], v168 offset:3072
	ds_read_b128 v[220:223], v168 offset:4096
	ds_read_b128 v[224:227], v168 offset:5120
	ds_read_b128 v[228:231], v168 offset:6144
	ds_read_b128 v[232:235], v168 offset:7168
	s_mov_b32 m0, s58
	s_nop 0
	global_load_lds_dwordx4 v[172:173], off
	s_mov_b32 m0, s59
	s_nop 0
	global_load_lds_dwordx4 v[240:241], off
	s_waitcnt vmcnt(8)
	s_waitcnt lgkmcnt(0)
	s_barrier
; #define PG8_STAGE(bufoff, gbase, voff) do { _Pragma("unroll") for (int _i = 0; _i < 2; ++_i) \
;         __builtin_amdgcn_global_load_lds((const unsigned*)((const char*)(gbase) + (voff)[_i]), (PG8_LAS unsigned*)(lds + (bufoff) + ldsw + _i * 8192), 16, 0, 0); } while (0)
; #define PG8_LDA(dst, b, h) do { _Pragma("unroll") for (int m = 0; m < 4; ++m) _Pragma("unroll") for (int k = 0; k < 2; ++k) dst[m][k] = *(const PG8_LAS bf16x8*)(lds + PG8_SA(b, h) + aoff + m * 2048 + k * 1024); } while (0)
; #define PG8_LDB(dst, b, h) do { _Pragma("unroll") for (int n = 0; n < 2; ++n) _Pragma("unroll") for (int k = 0; k < 2; ++k) dst[n][k] = *(const PG8_LAS bf16x8*)(lds + PG8_SB(b, h) + boff + n * 2048 + k * 1024); } while (0)
; #define PG8_MMA(ai, bj, At, Bt) do { __builtin_amdgcn_s_setprio(1); _Pragma("unroll") for (int m = 0; m < 4; ++m) _Pragma("unroll") for (int n = 0; n < 2; ++n) _Pragma("unroll") for (int k = 0; k < 2; ++k) \
;         acc[ai][bj][m][n] = __builtin_amdgcn_mfma_f32_16x16x32_bf16(Bt[n][k], At[m][k], acc[ai][bj][m][n], 0, 0, 0); __builtin_amdgcn_s_setprio(0); } while (0)
; #define PG8_WAIT_V(n) asm volatile("s_waitcnt vmcnt(" #n ")" ::: "memory")
; #define PG8_WAIT_L(n) asm volatile("s_waitcnt lgkmcnt(" #n ")" ::: "memory")
; #define PG8_BAR __builtin_amdgcn_s_barrier()
; #define PG8_SCHED __builtin_amdgcn_sched_barrier(0)
; template <class Epi, class Sched, bool ALIGN_EPI = false, bool SP2 = false, bool ABLK = false>
; __device__ __forceinline__ void gemm_phase(PG8_LAS unsigned char* lds, const Gemm g, const Sched& S, const Epi& E) {
;     ...
;             PG8_WAIT_V(8); PG8_WAIT_L(0); PG8_BAR; PG8_MMA(0, 0, At, B0); PG8_MMA(0, 1, At, B1); PG8_BAR; PG8_SCHED;
;             PG8_LDA(At, 0, 1); PG8_STAGE(PG8_SB(0, 0), b2, voffB); PG8_STAGE(PG8_SB(0, 1), b2 + hstep, voffB); PG8_STAGE(PG8_SA(0, 0), a2, voffA);
;             PG8_WAIT_V(8); PG8_WAIT_L(0); PG8_BAR; PG8_MMA(1, 0, At, B0); PG8_MMA(1, 1, At, B1); PG8_BAR; PG8_SCHED;
;             PG8_LDB(B0, 1, 0); PG8_LDB(B1, 1, 1); PG8_SCHED; PG8_LDA(At, 1, 0); PG8_STAGE(PG8_SA(0, 1), a2 + hstepA, voffA);
;             PG8_WAIT_V(8); PG8_WAIT_L(0); PG8_BAR; PG8_MMA(0, 0, At, B0); PG8_MMA(0, 1, At, B1); PG8_BAR; PG8_SCHED;
	s_setprio 1
	s_waitcnt lgkmcnt(0)
	v_mfma_f32_16x16x32_bf16 v[124:127], v[128:131], v[204:207], v[124:127]
	v_mfma_f32_16x16x32_bf16 v[120:123], v[180:183], v[204:207], v[120:123]
	v_mfma_f32_16x16x32_bf16 v[108:111], v[128:131], v[212:215], v[108:111]
	v_mfma_f32_16x16x32_bf16 v[104:107], v[180:183], v[212:215], v[104:107]
	v_mfma_f32_16x16x32_bf16 v[92:95], v[128:131], v[220:223], v[92:95]
	v_mfma_f32_16x16x32_bf16 v[88:91], v[180:183], v[220:223], v[88:91]
	v_mfma_f32_16x16x32_bf16 v[76:79], v[128:131], v[228:231], v[76:79]
	v_mfma_f32_16x16x32_bf16 v[72:75], v[180:183], v[228:231], v[72:75]
	s_setprio 0
	s_setprio 1
	v_mfma_f32_16x16x32_bf16 v[124:127], v[176:179], v[208:211], v[124:127]
	v_mfma_f32_16x16x32_bf16 v[120:123], v[184:187], v[208:211], v[120:123]
	v_mfma_f32_16x16x32_bf16 v[108:111], v[176:179], v[216:219], v[108:111]
	v_mfma_f32_16x16x32_bf16 v[104:107], v[184:187], v[216:219], v[104:107]
	v_mfma_f32_16x16x32_bf16 v[92:95], v[176:179], v[224:227], v[92:95]
	v_mfma_f32_16x16x32_bf16 v[88:91], v[184:187], v[224:227], v[88:91]
	v_mfma_f32_16x16x32_bf16 v[76:79], v[176:179], v[232:235], v[76:79]
	v_mfma_f32_16x16x32_bf16 v[72:75], v[184:187], v[232:235], v[72:75]
	s_setprio 0
	s_setprio 1
	v_mfma_f32_16x16x32_bf16 v[116:119], v[188:191], v[204:207], v[116:119]
	v_mfma_f32_16x16x32_bf16 v[112:115], v[196:199], v[204:207], v[112:115]
	v_mfma_f32_16x16x32_bf16 v[100:103], v[188:191], v[212:215], v[100:103]
	v_mfma_f32_16x16x32_bf16 v[96:99], v[196:199], v[212:215], v[96:99]
	v_mfma_f32_16x16x32_bf16 v[84:87], v[188:191], v[220:223], v[84:87]
	v_mfma_f32_16x16x32_bf16 v[80:83], v[196:199], v[220:223], v[80:83]
	v_mfma_f32_16x16x32_bf16 v[68:71], v[188:191], v[228:231], v[68:71]
	v_mfma_f32_16x16x32_bf16 v[64:67], v[196:199], v[228:231], v[64:67]
	s_setprio 0
	s_setprio 1
	v_mfma_f32_16x16x32_bf16 v[116:119], v[192:195], v[208:211], v[116:119]
	v_mfma_f32_16x16x32_bf16 v[112:115], v[200:203], v[208:211], v[112:115]
	v_mfma_f32_16x16x32_bf16 v[100:103], v[192:195], v[216:219], v[100:103]
	v_mfma_f32_16x16x32_bf16 v[96:99], v[200:203], v[216:219], v[96:99]
	v_mfma_f32_16x16x32_bf16 v[84:87], v[192:195], v[224:227], v[84:87]
	v_mfma_f32_16x16x32_bf16 v[80:83], v[200:203], v[224:227], v[80:83]
	v_mfma_f32_16x16x32_bf16 v[68:71], v[192:195], v[232:235], v[68:71]
	v_mfma_f32_16x16x32_bf16 v[64:67], v[200:203], v[232:235], v[64:67]
	s_setprio 0
	s_barrier
	s_add_u32 s70, s36, 0x40000
	s_addc_u32 s71, s37, 0
	s_add_i32 s2, s57, s3
	v_lshl_add_u64 v[172:173], s[36:37], 0, v[136:137]
	v_lshl_add_u64 v[236:237], s[36:37], 0, v[132:133]
	v_lshl_add_u64 v[238:239], s[70:71], 0, v[136:137]
	v_lshl_add_u64 v[240:241], s[70:71], 0, v[132:133]
	v_lshl_add_u64 v[242:243], s[38:39], 0, v[138:139]
	v_lshl_add_u64 v[254:255], s[38:39], 0, v[134:135]
	ds_read_b128 v[204:207], v168 offset:16384
	ds_read_b128 v[208:211], v168 offset:17408
	ds_read_b128 v[212:215], v168 offset:18432
	ds_read_b128 v[216:219], v168 offset:19456
	ds_read_b128 v[220:223], v168 offset:20480
	ds_read_b128 v[224:227], v168 offset:21504
	ds_read_b128 v[228:231], v168 offset:22528
	ds_read_b128 v[232:235], v168 offset:23552
	s_mov_b32 m0, s60
	s_nop 0
	global_load_lds_dwordx4 v[172:173], off
	s_add_i32 m0, s60, 0x2000
	s_nop 0
	global_load_lds_dwordx4 v[236:237], off
	s_mov_b32 m0, s2
	s_nop 0
	global_load_lds_dwordx4 v[238:239], off
	s_add_i32 m0, s2, 0x2000
	s_nop 0
	global_load_lds_dwordx4 v[240:241], off
	s_mov_b32 m0, s40
	s_nop 0
	global_load_lds_dwordx4 v[242:243], off
	s_mov_b32 m0, s41
	s_nop 0
	global_load_lds_dwordx4 v[254:255], off
	s_waitcnt vmcnt(8)
	s_waitcnt lgkmcnt(0)
	s_barrier
	s_setprio 1
	s_waitcnt lgkmcnt(0)
	v_mfma_f32_16x16x32_bf16 v[60:63], v[128:131], v[204:207], v[60:63]
	v_mfma_f32_16x16x32_bf16 v[56:59], v[180:183], v[204:207], v[56:59]
	v_mfma_f32_16x16x32_bf16 v[44:47], v[128:131], v[212:215], v[44:47]
	v_mfma_f32_16x16x32_bf16 v[40:43], v[180:183], v[212:215], v[40:43]
	v_mfma_f32_16x16x32_bf16 v[28:31], v[128:131], v[220:223], v[28:31]
	v_mfma_f32_16x16x32_bf16 v[24:27], v[180:183], v[220:223], v[24:27]
	v_mfma_f32_16x16x32_bf16 v[12:15], v[128:131], v[228:231], v[12:15]
	v_mfma_f32_16x16x32_bf16 v[8:11], v[180:183], v[228:231], v[8:11]
	s_setprio 0
	s_setprio 1
	v_mfma_f32_16x16x32_bf16 v[60:63], v[176:179], v[208:211], v[60:63]
	v_mfma_f32_16x16x32_bf16 v[56:59], v[184:187], v[208:211], v[56:59]
	v_mfma_f32_16x16x32_bf16 v[44:47], v[176:179], v[216:219], v[44:47]
	v_mfma_f32_16x16x32_bf16 v[40:43], v[184:187], v[216:219], v[40:43]
	v_mfma_f32_16x16x32_bf16 v[28:31], v[176:179], v[224:227], v[28:31]
	v_mfma_f32_16x16x32_bf16 v[24:27], v[184:187], v[224:227], v[24:27]
	v_mfma_f32_16x16x32_bf16 v[12:15], v[176:179], v[232:235], v[12:15]
	v_mfma_f32_16x16x32_bf16 v[8:11], v[184:187], v[232:235], v[8:11]
	s_setprio 0
	s_setprio 1
	v_mfma_f32_16x16x32_bf16 v[52:55], v[188:191], v[204:207], v[52:55]
	v_mfma_f32_16x16x32_bf16 v[48:51], v[196:199], v[204:207], v[48:51]
	v_mfma_f32_16x16x32_bf16 v[36:39], v[188:191], v[212:215], v[36:39]
	v_mfma_f32_16x16x32_bf16 v[32:35], v[196:199], v[212:215], v[32:35]
	v_mfma_f32_16x16x32_bf16 v[20:23], v[188:191], v[220:223], v[20:23]
	v_mfma_f32_16x16x32_bf16 v[16:19], v[196:199], v[220:223], v[16:19]
	v_mfma_f32_16x16x32_bf16 v[4:7], v[188:191], v[228:231], v[4:7]
	v_mfma_f32_16x16x32_bf16 v[0:3], v[196:199], v[228:231], v[0:3]
	s_setprio 0
	s_setprio 1
	v_mfma_f32_16x16x32_bf16 v[52:55], v[192:195], v[208:211], v[52:55]
	v_mfma_f32_16x16x32_bf16 v[48:51], v[200:203], v[208:211], v[48:51]
	v_mfma_f32_16x16x32_bf16 v[36:39], v[192:195], v[216:219], v[36:39]
	v_mfma_f32_16x16x32_bf16 v[32:35], v[200:203], v[216:219], v[32:35]
	v_mfma_f32_16x16x32_bf16 v[20:23], v[192:195], v[224:227], v[20:23]
	v_mfma_f32_16x16x32_bf16 v[16:19], v[200:203], v[224:227], v[16:19]
	v_mfma_f32_16x16x32_bf16 v[4:7], v[192:195], v[232:235], v[4:7]
	v_mfma_f32_16x16x32_bf16 v[0:3], v[200:203], v[232:235], v[0:3]
	s_setprio 0
	s_barrier
; #define PG8_STAGE(bufoff, gbase, voff) do { _Pragma("unroll") for (int _i = 0; _i < 2; ++_i) \
;         __builtin_amdgcn_global_load_lds((const unsigned*)((const char*)(gbase) + (voff)[_i]), (PG8_LAS unsigned*)(lds + (bufoff) + ldsw + _i * 8192), 16, 0, 0); } while (0)
; #define PG8_LDA(dst, b, h) do { _Pragma("unroll") for (int m = 0; m < 4; ++m) _Pragma("unroll") for (int k = 0; k < 2; ++k) dst[m][k] = *(const PG8_LAS bf16x8*)(lds + PG8_SA(b, h) + aoff + m * 2048 + k * 1024); } while (0)
; #define PG8_LDB(dst, b, h) do { _Pragma("unroll") for (int n = 0; n < 2; ++n) _Pragma("unroll") for (int k = 0; k < 2; ++k) dst[n][k] = *(const PG8_LAS bf16x8*)(lds + PG8_SB(b, h) + boff + n * 2048 + k * 1024); } while (0)
; #define PG8_MMA(ai, bj, At, Bt) do { __builtin_amdgcn_s_setprio(1); _Pragma("unroll") for (int m = 0; m < 4; ++m) _Pragma("unroll") for (int n = 0; n < 2; ++n) _Pragma("unroll") for (int k = 0; k < 2; ++k) \
;         acc[ai][bj][m][n] = __builtin_amdgcn_mfma_f32_16x16x32_bf16(Bt[n][k], At[m][k], acc[ai][bj][m][n], 0, 0, 0); __builtin_amdgcn_s_setprio(0); } while (0)
; #define PG8_WAIT_V(n) asm volatile("s_waitcnt vmcnt(" #n ")" ::: "memory")
; #define PG8_WAIT_L(n) asm volatile("s_waitcnt lgkmcnt(" #n ")" ::: "memory")
; #define PG8_BAR __builtin_amdgcn_s_barrier()
; #define PG8_SCHED __builtin_amdgcn_sched_barrier(0)
; template <class Epi, class Sched, bool ALIGN_EPI = false, bool SP2 = false, bool ABLK = false>
; __device__ __forceinline__ void gemm_phase(PG8_LAS unsigned char* lds, const Gemm g, const Sched& S, const Epi& E) {
;     ...
;             PG8_LDB(B0, 1, 0); PG8_LDB(B1, 1, 1); PG8_SCHED; PG8_LDA(At, 1, 0); PG8_STAGE(PG8_SA(0, 1), a2 + hstepA, voffA);
;             PG8_WAIT_V(8); PG8_WAIT_L(0); PG8_BAR; PG8_MMA(0, 0, At, B0); PG8_MMA(0, 1, At, B1); PG8_BAR; PG8_SCHED;
	s_add_i32 s2, 0, 0x18000
	v_add_u32_e32 v171, s2, v166
	s_add_i32 s70, 0, 0x1c000
	ds_read_b128 v[128:131], v171
	ds_read_b128 v[176:179], v171 offset:1024
	ds_read_b128 v[180:183], v171 offset:2048
	ds_read_b128 v[184:187], v171 offset:3072
	v_add_u32_e32 v171, s70, v166
	ds_read_b128 v[188:191], v171
	ds_read_b128 v[192:195], v171 offset:1024
	ds_read_b128 v[196:199], v171 offset:2048
	ds_read_b128 v[200:203], v171 offset:3072
	s_add_u32 s38, s38, 0x4000
	s_addc_u32 s39, s39, 0
	v_lshl_add_u64 v[238:239], s[38:39], 0, v[138:139]
	v_lshl_add_u64 v[240:241], s[38:39], 0, v[134:135]
	ds_read_b128 v[204:207], v168 offset:32768
	ds_read_b128 v[208:211], v168 offset:33792
	ds_read_b128 v[212:215], v168 offset:34816
	ds_read_b128 v[216:219], v168 offset:35840
	ds_read_b128 v[220:223], v168 offset:36864
	ds_read_b128 v[224:227], v168 offset:37888
	ds_read_b128 v[228:231], v168 offset:38912
	ds_read_b128 v[232:235], v168 offset:39936
	s_mov_b32 m0, s44
	s_nop 0
	global_load_lds_dwordx4 v[238:239], off
	s_mov_b32 m0, s45
	s_nop 0
	global_load_lds_dwordx4 v[240:241], off
	s_waitcnt vmcnt(8)
	s_waitcnt lgkmcnt(0)
	s_barrier
	s_setprio 1
	s_waitcnt lgkmcnt(0)
	v_mfma_f32_16x16x32_bf16 v[124:127], v[128:131], v[204:207], v[124:127]
	v_mfma_f32_16x16x32_bf16 v[120:123], v[180:183], v[204:207], v[120:123]
	v_mfma_f32_16x16x32_bf16 v[108:111], v[128:131], v[212:215], v[108:111]
	v_mfma_f32_16x16x32_bf16 v[104:107], v[180:183], v[212:215], v[104:107]
	v_mfma_f32_16x16x32_bf16 v[92:95], v[128:131], v[220:223], v[92:95]
	v_mfma_f32_16x16x32_bf16 v[88:91], v[180:183], v[220:223], v[88:91]
	v_mfma_f32_16x16x32_bf16 v[76:79], v[128:131], v[228:231], v[76:79]
	v_mfma_f32_16x16x32_bf16 v[72:75], v[180:183], v[228:231], v[72:75]
	s_setprio 0
	s_setprio 1
	v_mfma_f32_16x16x32_bf16 v[124:127], v[176:179], v[208:211], v[124:127]
	v_mfma_f32_16x16x32_bf16 v[120:123], v[184:187], v[208:211], v[120:123]
	v_mfma_f32_16x16x32_bf16 v[108:111], v[176:179], v[216:219], v[108:111]
	v_mfma_f32_16x16x32_bf16 v[104:107], v[184:187], v[216:219], v[104:107]
	v_mfma_f32_16x16x32_bf16 v[92:95], v[176:179], v[224:227], v[92:95]
	v_mfma_f32_16x16x32_bf16 v[88:91], v[184:187], v[224:227], v[88:91]
	v_mfma_f32_16x16x32_bf16 v[76:79], v[176:179], v[232:235], v[76:79]
	v_mfma_f32_16x16x32_bf16 v[72:75], v[184:187], v[232:235], v[72:75]
	s_setprio 0
	s_setprio 1
	v_mfma_f32_16x16x32_bf16 v[116:119], v[188:191], v[204:207], v[116:119]
	v_mfma_f32_16x16x32_bf16 v[112:115], v[196:199], v[204:207], v[112:115]
	v_mfma_f32_16x16x32_bf16 v[100:103], v[188:191], v[212:215], v[100:103]
	v_mfma_f32_16x16x32_bf16 v[96:99], v[196:199], v[212:215], v[96:99]
	v_mfma_f32_16x16x32_bf16 v[84:87], v[188:191], v[220:223], v[84:87]
	v_mfma_f32_16x16x32_bf16 v[80:83], v[196:199], v[220:223], v[80:83]
	v_mfma_f32_16x16x32_bf16 v[68:71], v[188:191], v[228:231], v[68:71]
	v_mfma_f32_16x16x32_bf16 v[64:67], v[196:199], v[228:231], v[64:67]
	s_setprio 0
	s_setprio 1
	v_mfma_f32_16x16x32_bf16 v[116:119], v[192:195], v[208:211], v[116:119]
	v_mfma_f32_16x16x32_bf16 v[112:115], v[200:203], v[208:211], v[112:115]
	v_mfma_f32_16x16x32_bf16 v[100:103], v[192:195], v[216:219], v[100:103]
	v_mfma_f32_16x16x32_bf16 v[96:99], v[200:203], v[216:219], v[96:99]
	v_mfma_f32_16x16x32_bf16 v[84:87], v[192:195], v[224:227], v[84:87]
	v_mfma_f32_16x16x32_bf16 v[80:83], v[200:203], v[224:227], v[80:83]
	v_mfma_f32_16x16x32_bf16 v[68:71], v[192:195], v[232:235], v[68:71]
	v_mfma_f32_16x16x32_bf16 v[64:67], v[200:203], v[232:235], v[64:67]
	s_setprio 0
	s_barrier
; #define PG8_STAGE(bufoff, gbase, voff) do { _Pragma("unroll") for (int _i = 0; _i < 2; ++_i) \
;         __builtin_amdgcn_global_load_lds((const unsigned*)((const char*)(gbase) + (voff)[_i]), (PG8_LAS unsigned*)(lds + (bufoff) + ldsw + _i * 8192), 16, 0, 0); } while (0)
; #define PG8_LDA(dst, b, h) do { _Pragma("unroll") for (int m = 0; m < 4; ++m) _Pragma("unroll") for (int k = 0; k < 2; ++k) dst[m][k] = *(const PG8_LAS bf16x8*)(lds + PG8_SA(b, h) + aoff + m * 2048 + k * 1024); } while (0)
; #define PG8_MMA(ai, bj, At, Bt) do { __builtin_amdgcn_s_setprio(1); _Pragma("unroll") for (int m = 0; m < 4; ++m) _Pragma("unroll") for (int n = 0; n < 2; ++n) _Pragma("unroll") for (int k = 0; k < 2; ++k) \
;         acc[ai][bj][m][n] = __builtin_amdgcn_mfma_f32_16x16x32_bf16(Bt[n][k], At[m][k], acc[ai][bj][m][n], 0, 0, 0); __builtin_amdgcn_s_setprio(0); } while (0)
; #define PG8_WAIT_V(n) asm volatile("s_waitcnt vmcnt(" #n ")" ::: "memory")
; #define PG8_WAIT_L(n) asm volatile("s_waitcnt lgkmcnt(" #n ")" ::: "memory")
; #define PG8_BAR __builtin_amdgcn_s_barrier()
; #define PG8_SCHED __builtin_amdgcn_sched_barrier(0)
; template <class Epi, class Sched, bool ALIGN_EPI = false, bool SP2 = false, bool ABLK = false>
; __device__ __forceinline__ void gemm_phase(PG8_LAS unsigned char* lds, const Gemm g, const Sched& S, const Epi& E) {
;     ...
;             PG8_LDA(At, 1, 1); PG8_STAGE(PG8_SB(1, 0), b3, voffB); PG8_STAGE(PG8_SB(1, 1), b3 + hstep, voffB); PG8_STAGE(PG8_SA(1, 0), a3, voffA);
;             PG8_WAIT_V(8); PG8_WAIT_L(0); PG8_BAR; PG8_MMA(1, 0, At, B0); PG8_MMA(1, 1, At, B1); PG8_BAR; PG8_SCHED;
	s_add_i32 s2, s2, s3
	s_add_u32 s36, s36, 0x40080
	s_addc_u32 s37, s37, 0
	v_lshl_add_u64 v[172:173], v[172:173], 0, s[16:17]
	v_lshl_add_u64 v[236:237], v[236:237], 0, s[16:17]
	v_lshl_add_u64 v[238:239], s[36:37], 0, v[136:137]
	v_lshl_add_u64 v[240:241], s[36:37], 0, v[132:133]
	v_lshl_add_u64 v[242:243], s[34:35], 0, v[138:139]
	v_lshl_add_u64 v[254:255], s[34:35], 0, v[134:135]
	ds_read_b128 v[204:207], v168 offset:49152
	ds_read_b128 v[208:211], v168 offset:50176
	ds_read_b128 v[212:215], v168 offset:51200
	ds_read_b128 v[216:219], v168 offset:52224
	ds_read_b128 v[220:223], v168 offset:53248
	ds_read_b128 v[224:227], v168 offset:54272
	ds_read_b128 v[228:231], v168 offset:55296
	ds_read_b128 v[232:235], v168 offset:56320
	s_mov_b32 m0, s2
	s_nop 0
	global_load_lds_dwordx4 v[172:173], off
	s_add_i32 m0, s2, 0x2000
	s_nop 0
	global_load_lds_dwordx4 v[236:237], off
	s_add_i32 s2, s70, s3
	s_mov_b32 m0, s2
	s_nop 0
	global_load_lds_dwordx4 v[238:239], off
	s_add_i32 m0, s2, 0x2000
	s_nop 0
	global_load_lds_dwordx4 v[240:241], off
	s_mov_b32 m0, s55
	s_nop 0
	global_load_lds_dwordx4 v[242:243], off
	s_mov_b32 m0, s56
	s_nop 0
	global_load_lds_dwordx4 v[254:255], off
	s_waitcnt vmcnt(8)
	s_waitcnt lgkmcnt(0)
	s_barrier
	s_setprio 1
	s_waitcnt lgkmcnt(0)
	v_mfma_f32_16x16x32_bf16 v[60:63], v[128:131], v[204:207], v[60:63]
	v_mfma_f32_16x16x32_bf16 v[56:59], v[180:183], v[204:207], v[56:59]
	v_mfma_f32_16x16x32_bf16 v[44:47], v[128:131], v[212:215], v[44:47]
	v_mfma_f32_16x16x32_bf16 v[40:43], v[180:183], v[212:215], v[40:43]
	v_mfma_f32_16x16x32_bf16 v[28:31], v[128:131], v[220:223], v[28:31]
	v_mfma_f32_16x16x32_bf16 v[24:27], v[180:183], v[220:223], v[24:27]
	v_mfma_f32_16x16x32_bf16 v[12:15], v[128:131], v[228:231], v[12:15]
	v_mfma_f32_16x16x32_bf16 v[8:11], v[180:183], v[228:231], v[8:11]
	s_setprio 0
	s_setprio 1
	v_mfma_f32_16x16x32_bf16 v[60:63], v[176:179], v[208:211], v[60:63]
	v_mfma_f32_16x16x32_bf16 v[56:59], v[184:187], v[208:211], v[56:59]
	v_mfma_f32_16x16x32_bf16 v[44:47], v[176:179], v[216:219], v[44:47]
	v_mfma_f32_16x16x32_bf16 v[40:43], v[184:187], v[216:219], v[40:43]
	v_mfma_f32_16x16x32_bf16 v[28:31], v[176:179], v[224:227], v[28:31]
	v_mfma_f32_16x16x32_bf16 v[24:27], v[184:187], v[224:227], v[24:27]
	v_mfma_f32_16x16x32_bf16 v[12:15], v[176:179], v[232:235], v[12:15]
	v_mfma_f32_16x16x32_bf16 v[8:11], v[184:187], v[232:235], v[8:11]
	s_setprio 0
	s_setprio 1
	v_mfma_f32_16x16x32_bf16 v[52:55], v[188:191], v[204:207], v[52:55]
	v_mfma_f32_16x16x32_bf16 v[48:51], v[196:199], v[204:207], v[48:51]
	v_mfma_f32_16x16x32_bf16 v[36:39], v[188:191], v[212:215], v[36:39]
	v_mfma_f32_16x16x32_bf16 v[32:35], v[196:199], v[212:215], v[32:35]
	v_mfma_f32_16x16x32_bf16 v[20:23], v[188:191], v[220:223], v[20:23]
	v_mfma_f32_16x16x32_bf16 v[16:19], v[196:199], v[220:223], v[16:19]
	v_mfma_f32_16x16x32_bf16 v[4:7], v[188:191], v[228:231], v[4:7]
	v_mfma_f32_16x16x32_bf16 v[0:3], v[196:199], v[228:231], v[0:3]
	s_setprio 0
	s_setprio 1
	v_mfma_f32_16x16x32_bf16 v[52:55], v[192:195], v[208:211], v[52:55]
	v_mfma_f32_16x16x32_bf16 v[48:51], v[200:203], v[208:211], v[48:51]
	v_mfma_f32_16x16x32_bf16 v[36:39], v[192:195], v[216:219], v[36:39]
	v_mfma_f32_16x16x32_bf16 v[32:35], v[200:203], v[216:219], v[32:35]
	v_mfma_f32_16x16x32_bf16 v[20:23], v[192:195], v[224:227], v[20:23]
	v_mfma_f32_16x16x32_bf16 v[16:19], v[200:203], v[224:227], v[16:19]
	v_mfma_f32_16x16x32_bf16 v[4:7], v[192:195], v[232:235], v[4:7]
	v_mfma_f32_16x16x32_bf16 v[0:3], v[200:203], v[232:235], v[0:3]
	s_setprio 0
	s_barrier
	s_add_i32 s63, s63, 2
	s_add_u32 s61, s61, 0x100
	s_addc_u32 s62, s62, 0
	s_add_u32 s8, s8, 0x10000
	s_addc_u32 s9, s9, 0
	s_cmp_gt_u32 s63, 13
	s_cbranch_scc0 .LBB0_534
